# skip the grid barrier after the last layer's PEER phase (nothing follows it): exit straight to s_endpgm when the loop-exit flag is set
# speedup vs baseline: 1.0096x; 1.0096x over previous
.LBB0_1338:
	s_or_b64 exec, exec, s[0:1]
	v_readlane_b32 s98, v249, 15
	s_nop 1
	s_cmp_lg_u32 s98, 0
	s_cbranch_scc1 .LBB0_1385
	s_waitcnt vmcnt(0)
	s_barrier
	s_mov_b64 s[0:1], exec
	v_readlane_b32 s2, v250, 41
	v_readlane_b32 s3, v250, 42
	s_and_b64 s[2:3], s[0:1], s[2:3]
	v_readlane_b32 s21, v251, 4
	v_readlane_b32 s22, v251, 5
	v_readlane_b32 s34, v247, 57
	v_readlane_b32 s35, v247, 58
	s_mov_b32 s17, 0x3000000
	s_mov_b32 s10, 0x3010000
	s_mov_b32 s11, 0x3020000
	s_mov_b32 s12, 0x3030000
	s_mov_b64 exec, s[2:3]
	s_cbranch_execnz .LBB0_1339
	s_getpc_b64 s[98:99]
